# grid-barrier spin loops poll 4x more often (s_sleep 8 -> 2)
# speedup vs baseline: 1.0021x; 1.0021x over previous
.Lxbc_190:
	s_and_b32 s18, s26, 0xff
	s_mov_b64 s[16:17], -1
	s_cmp_lg_u32 s18, 0
	s_mov_b64 s[18:19], -1
	s_sleep 2
	s_cbranch_scc1 .Lxbc_194
	v_mov_b64_e32 v[2:3], s[8:9]
	flat_load_dword v0, v[2:3] offset:512 sc1
	s_mov_b64 s[18:19], 0
	s_mov_b64 s[20:21], -1
	s_waitcnt vmcnt(0) lgkmcnt(0)
	v_cmp_eq_u32_e32 vcc, 0, v0
	s_and_saveexec_b64 s[22:23], vcc
	s_cmp_lt_u32 s26, 0x400001
	s_cselect_b64 s[18:19], -1, 0
	s_xor_b64 s[20:21], exec, -1
	s_and_b64 s[18:19], s[18:19], exec
	s_or_b64 exec, exec, s[22:23]

.Lxbc_204:
	s_and_b32 s14, s22, 0xff
	s_cmp_lg_u32 s14, 0
	s_mov_b64 s[16:17], -1
	s_sleep 2
	s_cbranch_scc0 .Lxbc_206
	s_mov_b64 s[18:19], -1
	s_and_saveexec_b64 s[20:21], s[16:17]
	s_cbranch_execz .Lxbc_203
	s_branch .Lxbc_209

.LBB0_1358:
	s_and_b32 s16, s24, 0xff
	s_mov_b64 s[14:15], -1
	s_cmp_lg_u32 s16, 0
	s_mov_b64 s[16:17], -1
	s_sleep 2
	s_cbranch_scc1 .LBB0_1362
	v_readlane_b32 s16, v159, 0
	v_readlane_b32 s17, v159, 1
	s_mov_b64 s[18:19], -1
	s_nop 0
	v_mov_b64_e32 v[2:3], s[16:17]
	flat_load_dword v0, v[2:3] offset:512 sc1
	s_mov_b64 s[16:17], 0
	s_waitcnt vmcnt(0) lgkmcnt(0)
	v_cmp_eq_u32_e32 vcc, 0, v0
	s_and_saveexec_b64 s[20:21], vcc
	s_cmp_lt_u32 s24, 0x400001
	s_cselect_b64 s[16:17], -1, 0
	s_xor_b64 s[18:19], exec, -1
	s_and_b64 s[16:17], s[16:17], exec
	s_or_b64 exec, exec, s[20:21]

.LBB0_1372:
	s_and_b32 s14, s24, 0xff
	s_cmp_lg_u32 s14, 0
	s_mov_b64 s[16:17], -1
	s_sleep 2
	s_cbranch_scc0 .LBB0_1374
	s_mov_b64 s[18:19], -1
	s_and_saveexec_b64 s[20:21], s[16:17]
	s_cbranch_execz .LBB0_1371
	s_branch .LBB0_1377
